# E1 + drop redundant acc zeroing pass per unit + merged carry queries in the scan epilogue
# baseline (speedup 1.0000x reference)
.LBB0_488:
	v_mov_b32_e32 v183, v165
	v_mov_b32_e32 v181, v165
	v_mov_b32_e32 v179, v165
	v_mov_b32_e32 v177, v165
	v_mov_b32_e32 v175, v165
	v_mov_b32_e32 v173, v165
	v_mov_b32_e32 v171, v165
	s_and_b32 s20, s63, 31
	v_lshlrev_b32_e32 v0, 1, v239
	s_and_b32 s53, s63, 0xffffffe0
	s_lshl_b32 s55, s62, 2
	v_cmp_gt_i32_e32 vcc, s20, v0
	v_mov_b32_e32 v30, 1.0
	v_mov_b32_e32 v31, 0
	v_mov_b32_e32 v29, 0
	v_mov_b32_e32 v27, 0
	v_mov_b32_e32 v25, 0
	v_mov_b32_e32 v23, 0
	v_mov_b32_e32 v21, 0
	v_mov_b32_e32 v19, 0
	v_mov_b32_e32 v17, 0
	v_mov_b32_e32 v28, 1.0
	v_mov_b32_e32 v26, 1.0
	v_mov_b32_e32 v24, 1.0
	v_mov_b32_e32 v22, 1.0
	v_mov_b32_e32 v20, 1.0
	v_mov_b32_e32 v18, 1.0
	v_mov_b32_e32 v16, 1.0
	s_and_saveexec_b64 s[8:9], vcc
	s_cbranch_execz .LBB0_534
	v_add_u32_e32 v2, s53, v0
	v_or_b32_e32 v204, 1, v0
	v_lshl_add_u32 v4, v2, 5, s55
	v_cmp_gt_i32_e64 s[60:61], s20, v204
	v_add_u32_e32 v204, 32, v4
	v_lshlrev_b32_e32 v208, 3, v238
	s_mov_b32 s21, 0x10000
	v_cndmask_b32_e64 v204, v4, v204, s[60:61]
.Lcarry_poll:
	global_load_dword v206, v4, s[34:35] sc1
	global_load_dword v210, v204, s[34:35] sc1
	s_waitcnt vmcnt(0)
	v_min_u32_e32 v206, v206, v210
	v_cmp_gt_u32_e32 vcc, 4, v206
	s_cbranch_vccz .Lcarry_ready
	s_sleep 1
	s_add_i32 s21, s21, -1
	s_cmp_lg_u32 s21, 0
	s_cbranch_scc1 .Lcarry_poll
.Lcarry_ready:
	v_lshl_add_u32 v2, v2, 13, v208
	v_add_u32_e32 v4, 0x2000, v2
	global_load_dwordx2 v[30:31], v2, s[30:31] sc1
	global_load_dwordx2 v[28:29], v2, s[30:31] offset:8 sc1
	global_load_dwordx2 v[26:27], v2, s[30:31] offset:16 sc1
	global_load_dwordx2 v[24:25], v2, s[30:31] offset:24 sc1
	global_load_dwordx2 v[22:23], v2, s[30:31] offset:32 sc1
	global_load_dwordx2 v[20:21], v2, s[30:31] offset:40 sc1
	global_load_dwordx2 v[18:19], v2, s[30:31] offset:48 sc1
	global_load_dwordx2 v[16:17], v2, s[30:31] offset:56 sc1
	s_and_saveexec_b64 s[64:65], s[60:61]
	global_load_dwordx2 v[204:205], v4, s[30:31] sc1
	global_load_dwordx2 v[206:207], v4, s[30:31] offset:8 sc1
	global_load_dwordx2 v[208:209], v4, s[30:31] offset:16 sc1
	global_load_dwordx2 v[210:211], v4, s[30:31] offset:24 sc1
	global_load_dwordx2 v[212:213], v4, s[30:31] offset:32 sc1
	global_load_dwordx2 v[214:215], v4, s[30:31] offset:40 sc1
	global_load_dwordx2 v[216:217], v4, s[30:31] offset:48 sc1
	global_load_dwordx2 v[218:219], v4, s[30:31] offset:56 sc1
	s_mov_b64 exec, s[64:65]
	s_waitcnt vmcnt(0)
	v_fmac_f32_e32 v31, 0, v30
	v_fmac_f32_e32 v29, 0, v28
	v_fmac_f32_e32 v27, 0, v26
	v_fmac_f32_e32 v25, 0, v24
	v_fmac_f32_e32 v23, 0, v22
	v_fmac_f32_e32 v21, 0, v20
	v_fmac_f32_e32 v19, 0, v18
	v_fmac_f32_e32 v17, 0, v16
	s_and_saveexec_b64 s[64:65], s[60:61]
	v_fmac_f32_e32 v205, v31, v204
	v_fmac_f32_e32 v207, v29, v206
	v_mul_f32_e32 v30, v30, v204
	v_fmac_f32_e32 v209, v27, v208
	v_mul_f32_e32 v28, v28, v206
	v_fmac_f32_e32 v211, v25, v210
	v_mul_f32_e32 v26, v26, v208
	v_fmac_f32_e32 v213, v23, v212
	v_mul_f32_e32 v24, v24, v210
	v_fmac_f32_e32 v215, v21, v214
	v_mul_f32_e32 v22, v22, v212
	v_mul_f32_e32 v20, v20, v214
	v_fmac_f32_e32 v217, v19, v216
	v_fmac_f32_e32 v219, v17, v218
	v_mul_f32_e32 v18, v18, v216
	v_mul_f32_e32 v16, v16, v218
	v_mov_b32_e32 v31, v205
	v_mov_b32_e32 v29, v207
	v_mov_b32_e32 v27, v209
	v_mov_b32_e32 v25, v211
	v_mov_b32_e32 v23, v213
	v_mov_b32_e32 v21, v215
	v_mov_b32_e32 v19, v217
	v_mov_b32_e32 v17, v219
	s_mov_b64 exec, s[64:65]
